# v25 + forgetting-attention bias LDS reads issued together (one wait instead of five)
# speedup vs baseline: 1.0172x; 1.0002x over previous
; #define LAS __attribute__((address_space(3)))
; __device__ __forceinline__ f32x2 pk_sub(f32x2 a, f32x2 b) { f32x2 r; asm("v_pk_add_f32 %0, %1, %2 neg_lo:[0,1] neg_hi:[0,1]" : "=v"(r) : "v"(a), "v"(b)); return r; }
; template <int TYPE  >
; __device__ __forceinline__ void attn_item(const Params& P, const int b, const int h, const int qt, LAS unsigned char* lds) {
;     ...
;                 if (TYPE == 1) { const LAS float* fb = (const LAS float*)(lds + so + KREG + VREG + wid * 256) + 8 * hh;
; #pragma unroll
;                     for (int j = 0; j < 8; ++j) {
;                         const f32x2 b0 = *(const LAS f32x2*)(fb + 16 * (j >> 2) + 2 * (j & 3)), b1 = *(const LAS f32x2*)(fb + 32 + 16 * (j >> 2) + 2 * (j & 3));
;                         const f32x2 x0 = pk_sub((f32x2){s0[2 * j], s0[2 * j + 1]}, b0), x1 = pk_sub((f32x2){s1[2 * j], s1[2 * j + 1]}, b1);
;                         s0[2 * j] = x0[0]; s0[2 * j + 1] = x0[1]; s1[2 * j] = x1[0]; s1[2 * j + 1] = x1[1]; }
;                     if (diag) {
; #pragma unroll
;                         for (int i = 0; i < 16; ++i) { const int key = key0 + 16 * (i >> 3) + (i & 7); if (key > tq) s0[i] = -1e30f; if (key + 32 > tq) s1[i] = -1e30f; } } }
.LBB0_1153:
	s_cmp_gt_i32 s16, s11
	s_cbranch_scc1 .LBB0_1159
	v_add_u32_e32 v0, s13, v187
	v_add_u32_e32 v70, 0, v0
	v_xad_u32 v74, v0, 32, 0
	ds_read_b128 v[66:69], v70
	ds_read_b128 v[70:73], v70 offset:8192
	ds_read_b128 v[130:133], v74
	ds_read_b128 v[134:137], v74 offset:8192
	v_xad_u32 v74, v0, 64, 0
	ds_read_b128 v[138:141], v74
	ds_read_b128 v[142:145], v74 offset:8192
	v_xor_b32_e32 v74, 0x60, v0
	v_add_u32_e32 v74, 0, v74
	ds_read_b128 v[156:159], v74
	ds_read_b128 v[176:179], v74 offset:8192
	v_xor_b32_e32 v74, 0x80, v0
	v_add_u32_e32 v74, 0, v74
	ds_read_b128 v[180:183], v74
	ds_read_b128 v[198:201], v74 offset:8192
	v_xor_b32_e32 v74, 0xa0, v0
	v_add_u32_e32 v74, 0, v74
	ds_read_b128 v[202:205], v74
	ds_read_b128 v[226:229], v74 offset:8192
	v_xor_b32_e32 v74, 0xc0, v0
	v_xor_b32_e32 v0, 0xe0, v0
	v_add_u32_e32 v74, 0, v74
	v_add_u32_e32 v0, 0, v0
	ds_read_b128 v[230:233], v74
	ds_read_b128 v[234:237], v74 offset:8192
	ds_read_b128 v[238:241], v0
	ds_read_b128 v[242:245], v0 offset:8192
	s_setprio 1
	s_waitcnt lgkmcnt(0)
	v_mfma_f32_32x32x16_bf16 v[82:97], v[66:69], v[98:101], 0
	v_mfma_f32_32x32x16_bf16 v[66:81], v[70:73], v[98:101], 0
	v_mfma_f32_32x32x16_bf16 v[82:97], v[130:133], v[102:105], v[82:97]
	v_mfma_f32_32x32x16_bf16 v[66:81], v[134:137], v[102:105], v[66:81]
	v_mfma_f32_32x32x16_bf16 v[82:97], v[138:141], v[106:109], v[82:97]
	v_mfma_f32_32x32x16_bf16 v[66:81], v[142:145], v[106:109], v[66:81]
	v_mfma_f32_32x32x16_bf16 v[82:97], v[156:159], v[110:113], v[82:97]
	v_mfma_f32_32x32x16_bf16 v[66:81], v[176:179], v[110:113], v[66:81]
	s_setprio 0
	s_setprio 1
	v_mfma_f32_32x32x16_bf16 v[82:97], v[180:183], v[114:117], v[82:97]
	v_mfma_f32_32x32x16_bf16 v[66:81], v[198:201], v[114:117], v[66:81]
	v_mfma_f32_32x32x16_bf16 v[82:97], v[202:205], v[118:121], v[82:97]
	v_mfma_f32_32x32x16_bf16 v[66:81], v[226:229], v[118:121], v[66:81]
	v_mfma_f32_32x32x16_bf16 v[82:97], v[230:233], v[122:125], v[82:97]
	v_mfma_f32_32x32x16_bf16 v[66:81], v[234:237], v[122:125], v[66:81]
	v_mfma_f32_32x32x16_bf16 v[82:97], v[238:241], v[126:129], v[82:97]
	v_mfma_f32_32x32x16_bf16 v[66:81], v[242:245], v[126:129], v[66:81]
	s_setprio 0
	v_add_u32_e32 v138, s13, v190
	v_add_u32_e32 v0, s13, v189
	v_xor_b32_e32 v139, 64, v138
	v_add_u32_e32 v0, 0, v0
	v_xor_b32_e32 v130, 32, v138
	v_add_u32_e32 v194, 0, v139
	v_xor_b32_e32 v138, 0x60, v138
	s_nop 7
	s_nop 7
	s_nop 3
	v_add_u32_e32 v193, 0, v130
	ds_read_b128 v[134:137], v0 offset:16384
	ds_read_b128 v[130:133], v193
	v_add_u32_e32 v195, 0, v138
	ds_read_b128 v[142:145], v194
	ds_read_b128 v[138:141], v195
	v_add_u32_e32 v156, s13, v191
	v_add_u32_e32 v184, 0x8000, v156
	ds_read2_b64 v[198:201], v184 offset1:1
	ds_read2_b64 v[202:205], v184 offset0:2 offset1:3
	ds_read2_b64 v[226:229], v184 offset0:16 offset1:17
	ds_read2_b64 v[230:233], v184 offset0:18 offset1:19
	ds_read2_b64 v[234:237], v184 offset0:8 offset1:9
	ds_read2_b64 v[238:241], v184 offset0:24 offset1:25
	ds_read2_b64 v[242:245], v184 offset0:10 offset1:11
	ds_read2_b64 v[246:249], v184 offset0:26 offset1:27
	s_cmp_lg_u32 s11, s16
	s_waitcnt lgkmcnt(0)
	v_pk_add_f32 v[82:83], v[82:83], v[198:199] neg_lo:[0,1] neg_hi:[0,1]
	v_pk_add_f32 v[158:159], v[66:67], v[226:227] neg_lo:[0,1] neg_hi:[0,1]
	v_pk_add_f32 v[156:157], v[84:85], v[200:201] neg_lo:[0,1] neg_hi:[0,1]
	v_pk_add_f32 v[84:85], v[68:69], v[228:229] neg_lo:[0,1] neg_hi:[0,1]
	v_pk_add_f32 v[68:69], v[86:87], v[202:203] neg_lo:[0,1] neg_hi:[0,1]
	v_pk_add_f32 v[86:87], v[88:89], v[204:205] neg_lo:[0,1] neg_hi:[0,1]
	v_pk_add_f32 v[160:161], v[70:71], v[230:231] neg_lo:[0,1] neg_hi:[0,1]
	v_pk_add_f32 v[70:71], v[72:73], v[232:233] neg_lo:[0,1] neg_hi:[0,1]
	v_pk_add_f32 v[72:73], v[90:91], v[234:235] neg_lo:[0,1] neg_hi:[0,1]
	v_pk_add_f32 v[88:89], v[92:93], v[236:237] neg_lo:[0,1] neg_hi:[0,1]
	v_pk_add_f32 v[90:91], v[74:75], v[238:239] neg_lo:[0,1] neg_hi:[0,1]
	v_pk_add_f32 v[74:75], v[76:77], v[240:241] neg_lo:[0,1] neg_hi:[0,1]
	v_pk_add_f32 v[76:77], v[94:95], v[242:243] neg_lo:[0,1] neg_hi:[0,1]
	v_pk_add_f32 v[94:95], v[78:79], v[246:247] neg_lo:[0,1] neg_hi:[0,1]
	v_pk_add_f32 v[92:93], v[96:97], v[244:245] neg_lo:[0,1] neg_hi:[0,1]
	v_pk_add_f32 v[78:79], v[80:81], v[248:249] neg_lo:[0,1] neg_hi:[0,1]
	s_cbranch_scc1 .LBB0_1156
	v_cndmask_b32_e64 v66, v82, v223, s[38:39]
	v_cndmask_b32_e64 v158, v158, v223, s[40:41]
	v_cndmask_b32_e64 v82, v66, v82, s[42:43]
	v_cndmask_b32_e64 v83, v223, v83, s[42:43]
	v_cndmask_b32_e64 v159, v159, v223, s[44:45]
	v_cndmask_b32_e64 v156, v156, v223, s[46:47]
	v_cndmask_b32_e64 v84, v84, v223, s[48:49]
	v_cndmask_b32_e64 v157, v157, v223, s[50:51]
	v_cndmask_b32_e64 v85, v85, v223, s[52:53]
	v_cndmask_b32_e64 v68, v68, v223, s[54:55]
	v_cndmask_b32_e64 v160, v160, v223, s[56:57]
	v_cndmask_b32_e64 v69, v69, v223, s[58:59]
	v_cndmask_b32_e64 v161, v161, v223, s[60:61]
	v_cndmask_b32_e64 v86, v86, v223, s[62:63]
	v_cndmask_b32_e64 v70, v70, v223, s[64:65]
	v_cndmask_b32_e64 v87, v87, v223, s[66:67]
	v_cndmask_b32_e64 v71, v71, v223, s[68:69]
	v_cndmask_b32_e64 v72, v72, v223, s[70:71]
	v_cndmask_b32_e64 v90, v90, v223, s[72:73]
	v_cndmask_b32_e64 v73, v73, v223, s[74:75]
	v_cndmask_b32_e64 v91, v91, v223, s[76:77]
	v_cndmask_b32_e64 v88, v88, v223, s[78:79]
	v_cndmask_b32_e64 v74, v74, v223, s[4:5]
	v_cndmask_b32_e64 v89, v89, v223, s[80:81]
	v_cndmask_b32_e64 v75, v75, v223, s[82:83]
	v_cndmask_b32_e64 v76, v76, v223, s[6:7]
	v_cndmask_b32_e64 v94, v94, v223, s[84:85]
	v_cndmask_b32_e64 v77, v77, v223, s[86:87]
	v_cndmask_b32_e64 v95, v95, v223, s[88:89]
	v_cndmask_b32_e64 v92, v92, v223, s[90:91]
	v_cndmask_b32_e64 v78, v78, v223, s[92:93]
	v_cndmask_b32_e64 v93, v93, v223, s[94:95]
	v_cndmask_b32_e64 v79, v79, v223, s[96:97]
